# mixer waits: SGU quarter loop waits once for all 10 loads (was wait-after-first-load); pool loop top leaves previous item's stores in flight (vmcnt(8))
# baseline (speedup 1.0000x reference)
; #define LAS __attribute__((address_space(3)))
; #define LDS_WAIT() asm volatile("s_waitcnt lgkmcnt(0)" ::: "memory")
; #define lane (hw_lane())
; __device__ __forceinline__ void pool_load(const bf16* proj, int it, int lane, v4u (&raw)[12]) {
;     const int chunk = it >> 4, g = (it >> 2) & 3, rq = it & 3; proj += (size_t)(chunk >> 6) * GAP_P;
;     const size_t R0 = (size_t)chunk * 128 + rq * 32; const int tseq = (int)(R0 & (SEQ - 1)), r = lane & 15, q = lane >> 4;
; #pragma unroll
;     for (int i = 0; i < 12; ++i) { const int row = q + 4 * i; raw[i] = (v4u){0u, 0u, 0u, 0u};
;         if (row >= 16 || tseq != 0) raw[i] = __builtin_nontemporal_load((const v4u*)(proj + (R0 + row - 16) * DIN + g * 128 + r * 8)); }
; }
; __device__ __forceinline__ void pool_item(LAS unsigned char* wl, const bf16* proj, bf16* ymix, const bf16* WpT, const float* pscale, int chunk, int g, int rq, int lane, v4u (&raw)[12], int nxt_it) {
;     ymix += (size_t)(chunk >> 6) * GAP_Y;
;     const size_t R0 = (size_t)chunk * 128 + rq * 32; const int tseq = (int)(R0 & (SEQ - 1));
;     const int r = lane & 15, q = lane >> 4, win = 2 << g;
; #pragma unroll
;     for (int i = 0; i < 12; ++i) *(LAS v4u*)(wl + (q + 4 * i) * PP + r * 16) = raw[i];
;     LDS_WAIT();
;     if (nxt_it >= 0) pool_load(proj, nxt_it, lane, raw);
.LBB0_499:
	v_readlane_b32 s4, v254, 44
	v_or_b32_e32 v86, 44, v80
	v_mov_b32_e32 v87, v193
	v_readlane_b32 s5, v254, 45
	v_mov_b64_e32 v[40:41], s[0:1]
	s_add_u32 s13, s20, 0x10900000
	v_lshl_add_u64 v[16:17], s[4:5], 0, v[86:87]
	v_mad_u64_u32 v[18:19], s[0:1], v16, s7, v[40:41]
	v_mov_b32_e32 v16, v19
	v_mad_u64_u32 v[16:17], s[0:1], v17, s7, v[16:17]
	v_readlane_b32 s0, v254, 48
	v_or_b32_e32 v90, 36, v80
	v_mov_b32_e32 v91, v193
	s_addc_u32 s14, s21, 0
	v_mov_b32_e32 v19, v16
	s_lshl_b32 s86, s0, 1
	v_or_b32_e32 v88, 40, v80
	v_mov_b32_e32 v89, v193
	v_lshl_add_u64 v[24:25], s[4:5], 0, v[90:91]
	v_lshl_add_u64 v[16:17], v[18:19], 0, s[86:87]
	v_lshl_add_u64 v[18:19], s[4:5], 0, v[88:89]
	v_mad_u64_u32 v[26:27], s[0:1], v24, s7, v[40:41]
	v_mad_u64_u32 v[20:21], s[0:1], v18, s7, v[40:41]
	v_mov_b32_e32 v24, v27
	v_mov_b32_e32 v18, v21
	v_mad_u64_u32 v[24:25], s[0:1], v25, s7, v[24:25]
	v_mad_u64_u32 v[18:19], s[0:1], v19, s7, v[18:19]
	v_mov_b32_e32 v27, v24
	v_or_b32_e32 v92, 32, v80
	v_mov_b32_e32 v93, v193
	v_lshl_add_u64 v[16:17], v[16:17], 0, v[192:193]
	v_mov_b32_e32 v21, v18
	v_lshl_add_u64 v[24:25], v[26:27], 0, s[86:87]
	v_lshl_add_u64 v[26:27], s[4:5], 0, v[92:93]
	v_add_co_u32_e32 v16, vcc, s83, v16
	v_lshl_add_u64 v[18:19], v[20:21], 0, s[86:87]
	v_mad_u64_u32 v[28:29], s[0:1], v26, s7, v[40:41]
	v_addc_co_u32_e32 v17, vcc, -1, v17, vcc
	v_lshl_add_u64 v[18:19], v[18:19], 0, v[192:193]
	v_mov_b32_e32 v26, v29
	v_add_co_u32_e32 v18, vcc, s83, v18
	v_mad_u64_u32 v[26:27], s[0:1], v27, s7, v[26:27]
	s_nop 0
	v_addc_co_u32_e32 v19, vcc, -1, v19, vcc
	v_lshl_add_u64 v[24:25], v[24:25], 0, v[192:193]
	v_mov_b32_e32 v29, v26
	v_add_co_u32_e32 v24, vcc, s83, v24
	v_lshl_add_u64 v[26:27], v[28:29], 0, s[86:87]
	s_nop 0
	v_addc_co_u32_e32 v25, vcc, -1, v25, vcc
	v_lshl_add_u64 v[26:27], v[26:27], 0, v[192:193]
	v_add_co_u32_e32 v26, vcc, s83, v26
	v_or_b32_e32 v94, 28, v80
	global_load_dwordx4 v[20:23], v[16:17], off nt
	s_nop 0
	global_load_dwordx4 v[16:19], v[18:19], off nt
	v_addc_co_u32_e32 v27, vcc, -1, v27, vcc
	global_load_dwordx4 v[36:39], v[24:25], off nt
	global_load_dwordx4 v[32:35], v[26:27], off nt
	v_or_b32_e32 v24, s4, v94
	v_mad_u64_u32 v[24:25], s[0:1], v24, s7, v[40:41]
	v_or_b32_e32 v96, 24, v80
	v_add_u32_e32 v25, s11, v25
	v_or_b32_e32 v26, s4, v96
	v_lshl_add_u64 v[24:25], v[24:25], 0, s[86:87]
	v_mad_u64_u32 v[26:27], s[0:1], v26, s7, v[40:41]
	v_or_b32_e32 v98, 20, v80
	v_lshl_add_u64 v[24:25], v[24:25], 0, v[192:193]
	v_add_u32_e32 v27, s11, v27
	v_or_b32_e32 v42, s4, v98
	v_add_co_u32_e32 v24, vcc, s83, v24
	v_lshl_add_u64 v[26:27], v[26:27], 0, s[86:87]
	v_mad_u64_u32 v[42:43], s[0:1], v42, s7, v[40:41]
	v_or_b32_e32 v100, 16, v80
	v_addc_co_u32_e32 v25, vcc, -1, v25, vcc
	v_lshl_add_u64 v[26:27], v[26:27], 0, v[192:193]
	v_add_u32_e32 v43, s11, v43
	v_or_b32_e32 v44, s4, v100
	v_add_co_u32_e32 v26, vcc, s83, v26
	v_lshl_add_u64 v[42:43], v[42:43], 0, s[86:87]
	v_mad_u64_u32 v[40:41], s[0:1], v44, s7, v[40:41]
	v_addc_co_u32_e32 v27, vcc, -1, v27, vcc
	v_lshl_add_u64 v[42:43], v[42:43], 0, v[192:193]
	v_add_u32_e32 v41, s11, v41
	v_add_co_u32_e32 v42, vcc, s83, v42
	v_lshl_add_u64 v[40:41], v[40:41], 0, s[86:87]
	s_nop 0
	v_addc_co_u32_e32 v43, vcc, -1, v43, vcc
	v_lshl_add_u64 v[40:41], v[40:41], 0, v[192:193]
	v_add_co_u32_e32 v40, vcc, s83, v40
	global_load_dwordx4 v[28:31], v[24:25], off nt
	s_nop 0
	global_load_dwordx4 v[24:27], v[26:27], off nt
	v_addc_co_u32_e32 v41, vcc, -1, v41, vcc
	global_load_dwordx4 v[44:47], v[42:43], off nt
	s_nop 0
	global_load_dwordx4 v[40:43], v[40:41], off nt
	v_and_b32_e32 v49, 15, v81
	v_lshlrev_b32_e32 v104, 3, v80
	v_lshlrev_b32_e32 v50, 4, v49
	v_mul_i32_i24_e32 v52, 0x110, v48
	v_or_b32_e32 v106, 1, v104
	v_lshlrev_b32_e32 v48, 3, v49
	v_mov_b32_e32 v49, s10
	s_movk_i32 s0, 0x880
	v_add_u32_e32 v95, s2, v50
	v_mul_u32_u24_e32 v51, 0x110, v80
	v_mul_u32_u24_e32 v53, 0x880, v80
	v_mul_u32_u24_e32 v54, 0x110, v106
	v_mad_u32_u24 v49, v80, s0, v49
	v_readlane_b32 s0, v255, 23
	v_or_b32_e32 v102, 4, v80
	v_or_b32_e32 v108, 2, v104
	v_or_b32_e32 v110, 3, v104
	v_or_b32_e32 v112, 4, v104
	v_or_b32_e32 v114, 5, v104
	v_or_b32_e32 v116, 6, v104
	v_or_b32_e32 v118, 7, v104
	v_add3_u32 v97, v49, v50, s0
	v_add_u32_e32 v99, v95, v51
	v_add_u32_e32 v101, v95, v52
	v_add_u32_e32 v103, v95, v53
	v_add_u32_e32 v105, v95, v54
	v_lshlrev_b32_e32 v120, 1, v48
	v_readlane_b32 s22, v254, 60
	s_waitcnt vmcnt(0)
.LBB0_500:
	s_add_i32 s15, s22, s77
	v_readlane_b32 s4, v254, 41
	s_cmp_ge_i32 s15, s4
	s_waitcnt vmcnt(8) lgkmcnt(0)
	ds_write_b128 v99, v[0:3]
	ds_write_b128 v99, v[4:7] offset:1088
	ds_write_b128 v99, v[8:11] offset:2176
	ds_write_b128 v101, v[12:15]
	ds_write_b128 v99, v[40:43] offset:4352
	ds_write_b128 v99, v[44:47] offset:5440
	ds_write_b128 v99, v[24:27] offset:6528
	ds_write_b128 v99, v[28:31] offset:7616
	ds_write_b128 v99, v[32:35] offset:8704
	ds_write_b128 v99, v[36:39] offset:9792
	ds_write_b128 v99, v[16:19] offset:10880
	ds_write_b128 v99, v[20:23] offset:11968
	s_cselect_b64 s[0:1], -1, 0
	s_cmp_lt_i32 s15, s4
	s_waitcnt lgkmcnt(0)
	s_cselect_b32 s23, s15, -1
	s_cmp_lt_i32 s23, 0
	s_cbranch_scc1 .LBB0_505
	s_lshr_b32 s4, s23, 10
	s_lshr_b32 s86, s23, 4
	s_mul_hi_u32 s5, s4, 0x1400000
	s_mul_i32 s4, s4, 0x1400000
	s_add_u32 s10, s9, s4
	s_addc_u32 s11, s12, s5
	s_lshl_b32 s23, s23, 5
	s_lshl_b64 s[4:5], s[86:87], 7
	s_and_b32 s6, s23, 0x60
	s_or_b32 s4, s4, s6
	s_and_b32 s86, s4, 0x1fe0
	s_and_b32 s23, s23, 0x180
	s_cmp_eq_u64 s[86:87], 0
	s_cbranch_scc1 .LBB0_503
	v_or_b32_e32 v0, s4, v80
	v_mov_b64_e32 v[8:9], s[10:11]
	v_mad_u64_u32 v[0:1], s[24:25], v0, s7, v[8:9]
	v_mad_u32_u24 v1, s5, v242, v1
	s_lshl_b32 s86, s23, 1
	v_or_b32_e32 v2, s4, v102
	v_lshl_add_u64 v[0:1], v[0:1], 0, s[86:87]
	v_mad_u64_u32 v[2:3], s[24:25], v2, s7, v[8:9]
	v_lshl_add_u64 v[0:1], v[0:1], 0, v[192:193]
	v_mad_u32_u24 v3, s5, v242, v3
	v_or_b32_e32 v10, s4, v82
	v_or_b32_e32 v12, s4, v84
	v_add_co_u32_e32 v0, vcc, s83, v0
	v_lshl_add_u64 v[2:3], v[2:3], 0, s[86:87]
	v_mad_u64_u32 v[10:11], s[24:25], v10, s7, v[8:9]
	v_mad_u64_u32 v[8:9], s[24:25], v12, s7, v[8:9]
	v_addc_co_u32_e32 v1, vcc, -1, v1, vcc
	v_lshl_add_u64 v[2:3], v[2:3], 0, v[192:193]
	v_mad_u32_u24 v11, s5, v242, v11
	v_or_b32_e32 v13, s5, v85
	v_mov_b32_e32 v12, v9
	v_add_co_u32_e32 v4, vcc, s83, v2
	v_lshl_add_u64 v[10:11], v[10:11], 0, s[86:87]
	v_mad_u64_u32 v[12:13], s[24:25], v13, s7, v[12:13]
	v_addc_co_u32_e32 v5, vcc, -1, v3, vcc
	v_lshl_add_u64 v[10:11], v[10:11], 0, v[192:193]
	v_mov_b32_e32 v9, v12
	v_add_co_u32_e32 v10, vcc, s83, v10
	v_lshl_add_u64 v[8:9], v[8:9], 0, s[86:87]
	s_nop 0
	v_addc_co_u32_e32 v11, vcc, -1, v11, vcc
	v_lshl_add_u64 v[8:9], v[8:9], 0, v[192:193]
	v_add_co_u32_e32 v12, vcc, 0xffff4000, v8
	global_load_dwordx4 v[0:3], v[0:1], off nt
	s_nop 0
	global_load_dwordx4 v[4:7], v[4:5], off nt
	v_addc_co_u32_e32 v13, vcc, -1, v9, vcc
	global_load_dwordx4 v[8:11], v[10:11], off nt
	s_nop 0
	global_load_dwordx4 v[12:15], v[12:13], off nt
	s_branch .LBB0_504

; #define LAS __attribute__((address_space(3)))
; __device__ __forceinline__ unsigned pk2(float lo, float hi) { return f2bf(lo) | (f2bf(hi) << 16); }
; __device__ __forceinline__ float bflo(unsigned w) { return __uint_as_float(w << 16); }
; __device__ __forceinline__ float bfhi(unsigned w) { return __uint_as_float(w & 0xffff0000u); }
; __device__ __forceinline__ void sgu_item(LAS unsigned char* wl, const bf16* proj, bf16* ymix, const float* vstat, const float* sgu_g, const bf16* Wm, const float* sgu_b, int chunk, int h, int lane) {
;     ...
;     for (int dq = 0; dq < 4; ++dq) {
;         const int colv = h * 128 + dq * 32;
;         v4u raw[8];
; #pragma unroll
;         for (int i = 0; i < 8; ++i) raw[i] = __builtin_nontemporal_load((const v4u*)(proj + (R0 + rsub + 16 * i) * DIN + 1024 + colv + c16 * 8));
;         const f32x4 g0 = *(const f32x4*)(sgu_g + colv + c16 * 8), g1 = *(const f32x4*)(sgu_g + colv + c16 * 8 + 4);
; #pragma unroll
;         for (int i = 0; i < 8; ++i) { const int s = rsub + 16 * i; const f32x2 ms = st[s]; const v4u w = raw[i];
;             v2u lo, hi; lo.x = pk2((bflo(w.x) - ms.x) * ms.y * g0[0], (bfhi(w.x) - ms.x) * ms.y * g0[1]); lo.y = pk2((bflo(w.y) - ms.x) * ms.y * g0[2], (bfhi(w.y) - ms.x) * ms.y * g0[3]);
;             hi.x = pk2((bflo(w.z) - ms.x) * ms.y * g1[0], (bfhi(w.z) - ms.x) * ms.y * g1[1]); hi.y = pk2((bflo(w.w) - ms.x) * ms.y * g1[2], (bfhi(w.w) - ms.x) * ms.y * g1[3]);
;             *(LAS v2u*)(wl + s * VP2 + (4 * c16) * 2) = lo; *(LAS v2u*)(wl + s * VP2 + (16 + 4 * c16) * 2) = hi; }
.LBB0_511:
	v_lshl_add_u64 v[80:81], v[198:199], 0, s[20:21]
	v_add_co_u32_e32 v82, vcc, 0xf100000, v80
	s_mov_b32 s0, 0xf100000
	s_nop 0
	v_addc_co_u32_e32 v83, vcc, 0, v81, vcc
	global_load_dwordx4 v[118:121], v[82:83], off offset:2048 nt
	v_add_co_u32_e32 v82, vcc, 0xf10c000, v80
	s_waitcnt lgkmcnt(0)
	s_nop 0
	v_addc_co_u32_e32 v83, vcc, 0, v81, vcc
	global_load_dwordx4 v[112:115], v[82:83], off offset:2048 nt
	v_add_co_u32_e32 v82, vcc, 0xf118000, v80
	s_nop 0
	s_nop 0
	v_addc_co_u32_e32 v83, vcc, 0, v81, vcc
	global_load_dwordx4 v[108:111], v[82:83], off offset:2048 nt
	v_add_co_u32_e32 v82, vcc, 0xf124000, v80
	s_nop 0
	s_nop 0
	v_addc_co_u32_e32 v83, vcc, 0, v81, vcc
	global_load_dwordx4 v[104:107], v[82:83], off offset:2048 nt
	v_add_co_u32_e32 v82, vcc, 0xf130000, v80
	s_nop 0
	s_nop 0
	v_addc_co_u32_e32 v83, vcc, 0, v81, vcc
	global_load_dwordx4 v[100:103], v[82:83], off offset:2048 nt
	v_add_co_u32_e32 v82, vcc, 0xf13c000, v80
	s_nop 1
	v_addc_co_u32_e32 v83, vcc, 0, v81, vcc
	global_load_dwordx4 v[96:99], v[82:83], off offset:2048 nt
	v_add_co_u32_e32 v82, vcc, 0xf148000, v80
	s_nop 1
	v_addc_co_u32_e32 v83, vcc, 0, v81, vcc
	v_add_co_u32_e32 v80, vcc, 0xf154000, v80
	global_load_dwordx4 v[84:87], v[82:83], off offset:2048 nt
	s_nop 0
	v_addc_co_u32_e32 v81, vcc, 0, v81, vcc
	global_load_dwordx4 v[80:83], v[80:81], off offset:2048 nt
	s_nop 0
	global_load_dwordx4 v[88:91], v[178:179], off
	global_load_dwordx4 v[92:95], v[178:179], off offset:-16
	s_waitcnt vmcnt(0)
	v_lshlrev_b32_e32 v117, 16, v119
	v_lshlrev_b32_e32 v116, 16, v118
	v_and_b32_e32 v119, 0xffff0000, v119
	v_and_b32_e32 v118, 0xffff0000, v118
	ds_read_b64 v[122:123], v218 offset:10240
	v_lshl_add_u64 v[178:179], v[178:179], 0, s[88:89]
	s_waitcnt lgkmcnt(0)
	v_pk_add_f32 v[116:117], v[116:117], v[122:123] op_sel_hi:[1,0] neg_lo:[0,1] neg_hi:[0,1]
	s_nop 0
	v_pk_mul_f32 v[124:125], v[122:123], v[116:117] op_sel:[1,0]
	v_pk_add_f32 v[118:119], v[118:119], v[122:123] op_sel_hi:[1,0] neg_lo:[0,1] neg_hi:[0,1]
	s_waitcnt vmcnt(0)
	v_mov_b32_e32 v116, v92
	v_mov_b32_e32 v117, v94
	v_pk_mul_f32 v[124:125], v[116:117], v[124:125]
	v_pk_mul_f32 v[118:119], v[122:123], v[118:119] op_sel:[1,0]
	v_mov_b32_e32 v94, v93
	v_pk_mul_f32 v[92:93], v[94:95], v[118:119]
	v_and_b32_sdwa v118, v125, v245 dst_sel:DWORD dst_unused:UNUSED_PAD src0_sel:WORD_1 src1_sel:DWORD
	v_and_b32_sdwa v119, v124, v245 dst_sel:DWORD dst_unused:UNUSED_PAD src0_sel:WORD_1 src1_sel:DWORD
	v_add3_u32 v124, v124, v119, s68
	v_add3_u32 v118, v125, v118, s68
	v_and_b32_sdwa v119, v93, v245 dst_sel:DWORD dst_unused:UNUSED_PAD src0_sel:WORD_1 src1_sel:DWORD
	v_and_b32_sdwa v125, v92, v245 dst_sel:DWORD dst_unused:UNUSED_PAD src0_sel:WORD_1 src1_sel:DWORD
	v_add3_u32 v93, v93, v119, s68
	v_add3_u32 v92, v92, v125, s68
	v_and_b32_e32 v93, 0xffff0000, v93
	v_and_b32_e32 v92, 0xffff0000, v92
	v_or_b32_sdwa v119, v93, v118 dst_sel:DWORD dst_unused:UNUSED_PAD src0_sel:DWORD src1_sel:WORD_1
	v_or_b32_sdwa v118, v92, v124 dst_sel:DWORD dst_unused:UNUSED_PAD src0_sel:DWORD src1_sel:WORD_1
	v_lshlrev_b32_e32 v93, 16, v121
	v_lshlrev_b32_e32 v92, 16, v120
	v_and_b32_e32 v121, 0xffff0000, v121
	v_and_b32_e32 v120, 0xffff0000, v120
	v_pk_add_f32 v[92:93], v[92:93], v[122:123] op_sel_hi:[1,0] neg_lo:[0,1] neg_hi:[0,1]
	v_pk_add_f32 v[120:121], v[120:121], v[122:123] op_sel_hi:[1,0] neg_lo:[0,1] neg_hi:[0,1]
	v_pk_mul_f32 v[124:125], v[122:123], v[92:93] op_sel:[1,0]
	v_mov_b32_e32 v93, v90
	v_pk_mul_f32 v[120:121], v[122:123], v[120:121] op_sel:[1,0]
	v_mov_b32_e32 v90, v89
	v_mov_b32_e32 v92, v88
	v_pk_mul_f32 v[88:89], v[90:91], v[120:121]
	v_pk_mul_f32 v[124:125], v[92:93], v[124:125]
	v_and_b32_sdwa v122, v89, v245 dst_sel:DWORD dst_unused:UNUSED_PAD src0_sel:WORD_1 src1_sel:DWORD
	v_and_b32_sdwa v123, v88, v245 dst_sel:DWORD dst_unused:UNUSED_PAD src0_sel:WORD_1 src1_sel:DWORD
	v_and_b32_sdwa v120, v125, v245 dst_sel:DWORD dst_unused:UNUSED_PAD src0_sel:WORD_1 src1_sel:DWORD
	v_and_b32_sdwa v121, v124, v245 dst_sel:DWORD dst_unused:UNUSED_PAD src0_sel:WORD_1 src1_sel:DWORD
	v_add3_u32 v89, v89, v122, s68
	v_add3_u32 v88, v88, v123, s68
	v_add3_u32 v121, v124, v121, s68
	v_add3_u32 v120, v125, v120, s68
	v_and_b32_e32 v89, 0xffff0000, v89
	v_and_b32_e32 v88, 0xffff0000, v88
	v_or_b32_sdwa v89, v89, v120 dst_sel:DWORD dst_unused:UNUSED_PAD src0_sel:DWORD src1_sel:WORD_1
	v_or_b32_sdwa v88, v88, v121 dst_sel:DWORD dst_unused:UNUSED_PAD src0_sel:DWORD src1_sel:WORD_1
	ds_write2_b64 v219, v[118:119], v[88:89] offset1:4
	ds_read_b64 v[88:89], v218 offset:10368
	v_lshlrev_b32_e32 v119, 16, v113
	v_lshlrev_b32_e32 v118, 16, v112
	v_and_b32_e32 v113, 0xffff0000, v113
	v_and_b32_e32 v112, 0xffff0000, v112
	s_waitcnt lgkmcnt(0)
; #define LAS __attribute__((address_space(3)))
; __device__ __forceinline__ unsigned pk2(float lo, float hi) { return f2bf(lo) | (f2bf(hi) << 16); }
; __device__ __forceinline__ float bflo(unsigned w) { return __uint_as_float(w << 16); }
; __device__ __forceinline__ float bfhi(unsigned w) { return __uint_as_float(w & 0xffff0000u); }
; __device__ __forceinline__ void sgu_item(LAS unsigned char* wl, const bf16* proj, bf16* ymix, const float* vstat, const float* sgu_g, const bf16* Wm, const float* sgu_b, int chunk, int h, int lane) {
;     ...
;         for (int i = 0; i < 8; ++i) { const int s = rsub + 16 * i; const f32x2 ms = st[s]; const v4u w = raw[i];
;             v2u lo, hi; lo.x = pk2((bflo(w.x) - ms.x) * ms.y * g0[0], (bfhi(w.x) - ms.x) * ms.y * g0[1]); lo.y = pk2((bflo(w.y) - ms.x) * ms.y * g0[2], (bfhi(w.y) - ms.x) * ms.y * g0[3]);
;             hi.x = pk2((bflo(w.z) - ms.x) * ms.y * g1[0], (bfhi(w.z) - ms.x) * ms.y * g1[1]); hi.y = pk2((bflo(w.w) - ms.x) * ms.y * g1[2], (bfhi(w.w) - ms.x) * ms.y * g1[3]);
;             *(LAS v2u*)(wl + s * VP2 + (4 * c16) * 2) = lo; *(LAS v2u*)(wl + s * VP2 + (16 + 4 * c16) * 2) = hi; }
	v_pk_add_f32 v[118:119], v[118:119], v[88:89] op_sel_hi:[1,0] neg_lo:[0,1] neg_hi:[0,1]
	v_pk_add_f32 v[112:113], v[112:113], v[88:89] op_sel_hi:[1,0] neg_lo:[0,1] neg_hi:[0,1]
	v_pk_mul_f32 v[118:119], v[88:89], v[118:119] op_sel:[1,0]
	v_pk_mul_f32 v[112:113], v[88:89], v[112:113] op_sel:[1,0]
	v_pk_mul_f32 v[118:119], v[116:117], v[118:119]
	v_pk_mul_f32 v[112:113], v[94:95], v[112:113]
	v_and_b32_sdwa v120, v119, v245 dst_sel:DWORD dst_unused:UNUSED_PAD src0_sel:WORD_1 src1_sel:DWORD
	v_and_b32_sdwa v121, v118, v245 dst_sel:DWORD dst_unused:UNUSED_PAD src0_sel:WORD_1 src1_sel:DWORD
	v_add3_u32 v118, v118, v121, s68
	v_add3_u32 v119, v119, v120, s68
	v_and_b32_sdwa v120, v113, v245 dst_sel:DWORD dst_unused:UNUSED_PAD src0_sel:WORD_1 src1_sel:DWORD
	v_and_b32_sdwa v121, v112, v245 dst_sel:DWORD dst_unused:UNUSED_PAD src0_sel:WORD_1 src1_sel:DWORD
	v_add3_u32 v113, v113, v120, s68
	v_add3_u32 v112, v112, v121, s68
	v_and_b32_e32 v113, 0xffff0000, v113
	v_and_b32_e32 v112, 0xffff0000, v112
	v_or_b32_sdwa v113, v113, v119 dst_sel:DWORD dst_unused:UNUSED_PAD src0_sel:DWORD src1_sel:WORD_1
	v_or_b32_sdwa v112, v112, v118 dst_sel:DWORD dst_unused:UNUSED_PAD src0_sel:DWORD src1_sel:WORD_1
	v_lshlrev_b32_e32 v119, 16, v115
	v_lshlrev_b32_e32 v118, 16, v114
	v_pk_add_f32 v[118:119], v[118:119], v[88:89] op_sel_hi:[1,0] neg_lo:[0,1] neg_hi:[0,1]
	v_and_b32_e32 v115, 0xffff0000, v115
	v_and_b32_e32 v114, 0xffff0000, v114
	v_pk_mul_f32 v[118:119], v[88:89], v[118:119] op_sel:[1,0]
	v_pk_add_f32 v[114:115], v[114:115], v[88:89] op_sel_hi:[1,0] neg_lo:[0,1] neg_hi:[0,1]
	v_pk_mul_f32 v[118:119], v[92:93], v[118:119]
	v_pk_mul_f32 v[88:89], v[88:89], v[114:115] op_sel:[1,0]
	v_and_b32_sdwa v114, v119, v245 dst_sel:DWORD dst_unused:UNUSED_PAD src0_sel:WORD_1 src1_sel:DWORD
	v_pk_mul_f32 v[88:89], v[90:91], v[88:89]
	v_and_b32_sdwa v115, v118, v245 dst_sel:DWORD dst_unused:UNUSED_PAD src0_sel:WORD_1 src1_sel:DWORD
	v_add3_u32 v115, v118, v115, s68
	v_add3_u32 v114, v119, v114, s68
	v_and_b32_sdwa v118, v89, v245 dst_sel:DWORD dst_unused:UNUSED_PAD src0_sel:WORD_1 src1_sel:DWORD
	v_and_b32_sdwa v119, v88, v245 dst_sel:DWORD dst_unused:UNUSED_PAD src0_sel:WORD_1 src1_sel:DWORD
	v_add3_u32 v89, v89, v118, s68
	v_add3_u32 v88, v88, v119, s68
	v_and_b32_e32 v89, 0xffff0000, v89
	v_and_b32_e32 v88, 0xffff0000, v88
	v_or_b32_sdwa v89, v89, v114 dst_sel:DWORD dst_unused:UNUSED_PAD src0_sel:DWORD src1_sel:WORD_1
	v_or_b32_sdwa v88, v88, v115 dst_sel:DWORD dst_unused:UNUSED_PAD src0_sel:DWORD src1_sel:WORD_1
	ds_write2_b64 v219, v[112:113], v[88:89] offset0:160 offset1:164
	ds_read_b64 v[112:113], v218 offset:10496
	v_lshlrev_b32_e32 v89, 16, v109
	v_lshlrev_b32_e32 v88, 16, v108
	v_and_b32_e32 v109, 0xffff0000, v109
	v_and_b32_e32 v108, 0xffff0000, v108
	s_waitcnt lgkmcnt(0)
	v_pk_add_f32 v[88:89], v[88:89], v[112:113] op_sel_hi:[1,0] neg_lo:[0,1] neg_hi:[0,1]
	v_pk_add_f32 v[108:109], v[108:109], v[112:113] op_sel_hi:[1,0] neg_lo:[0,1] neg_hi:[0,1]
	v_pk_mul_f32 v[88:89], v[112:113], v[88:89] op_sel:[1,0]
	v_pk_mul_f32 v[108:109], v[112:113], v[108:109] op_sel:[1,0]
	v_pk_mul_f32 v[88:89], v[116:117], v[88:89]
	v_pk_mul_f32 v[108:109], v[94:95], v[108:109]
	v_and_b32_sdwa v114, v89, v245 dst_sel:DWORD dst_unused:UNUSED_PAD src0_sel:WORD_1 src1_sel:DWORD
	v_and_b32_sdwa v115, v88, v245 dst_sel:DWORD dst_unused:UNUSED_PAD src0_sel:WORD_1 src1_sel:DWORD
	v_add3_u32 v88, v88, v115, s68
	v_add3_u32 v89, v89, v114, s68
	v_and_b32_sdwa v114, v109, v245 dst_sel:DWORD dst_unused:UNUSED_PAD src0_sel:WORD_1 src1_sel:DWORD
	v_and_b32_sdwa v115, v108, v245 dst_sel:DWORD dst_unused:UNUSED_PAD src0_sel:WORD_1 src1_sel:DWORD
	v_add3_u32 v109, v109, v114, s68
	v_add3_u32 v108, v108, v115, s68
	v_and_b32_e32 v109, 0xffff0000, v109
	v_and_b32_e32 v108, 0xffff0000, v108
	v_or_b32_sdwa v89, v109, v89 dst_sel:DWORD dst_unused:UNUSED_PAD src0_sel:DWORD src1_sel:WORD_1
	v_or_b32_sdwa v88, v108, v88 dst_sel:DWORD dst_unused:UNUSED_PAD src0_sel:DWORD src1_sel:WORD_1
	v_lshlrev_b32_e32 v109, 16, v111
	v_lshlrev_b32_e32 v108, 16, v110
	v_pk_add_f32 v[108:109], v[108:109], v[112:113] op_sel_hi:[1,0] neg_lo:[0,1] neg_hi:[0,1]
	v_and_b32_e32 v111, 0xffff0000, v111
	v_and_b32_e32 v110, 0xffff0000, v110
	v_pk_mul_f32 v[108:109], v[112:113], v[108:109] op_sel:[1,0]
	v_pk_add_f32 v[110:111], v[110:111], v[112:113] op_sel_hi:[1,0] neg_lo:[0,1] neg_hi:[0,1]
	v_pk_mul_f32 v[108:109], v[92:93], v[108:109]
	v_pk_mul_f32 v[110:111], v[112:113], v[110:111] op_sel:[1,0]
	v_and_b32_sdwa v112, v109, v245 dst_sel:DWORD dst_unused:UNUSED_PAD src0_sel:WORD_1 src1_sel:DWORD
	v_pk_mul_f32 v[110:111], v[90:91], v[110:111]
	v_and_b32_sdwa v113, v108, v245 dst_sel:DWORD dst_unused:UNUSED_PAD src0_sel:WORD_1 src1_sel:DWORD
	v_add3_u32 v108, v108, v113, s68
	v_add3_u32 v109, v109, v112, s68
	v_and_b32_sdwa v112, v111, v245 dst_sel:DWORD dst_unused:UNUSED_PAD src0_sel:WORD_1 src1_sel:DWORD
	v_and_b32_sdwa v113, v110, v245 dst_sel:DWORD dst_unused:UNUSED_PAD src0_sel:WORD_1 src1_sel:DWORD
	v_add3_u32 v111, v111, v112, s68
	v_add3_u32 v110, v110, v113, s68
	v_and_b32_e32 v111, 0xffff0000, v111
	v_and_b32_e32 v110, 0xffff0000, v110
	v_or_b32_sdwa v109, v111, v109 dst_sel:DWORD dst_unused:UNUSED_PAD src0_sel:DWORD src1_sel:WORD_1
	v_or_b32_sdwa v108, v110, v108 dst_sel:DWORD dst_unused:UNUSED_PAD src0_sel:DWORD src1_sel:WORD_1
	v_add_u32_e32 v110, 0x800, v219
	ds_write2_b64 v110, v[88:89], v[108:109] offset0:64 offset1:68
	ds_read_b64 v[88:89], v218 offset:10624
	v_lshlrev_b32_e32 v109, 16, v105
	v_lshlrev_b32_e32 v108, 16, v104
	v_and_b32_e32 v105, 0xffff0000, v105
	v_and_b32_e32 v104, 0xffff0000, v104
	s_waitcnt lgkmcnt(0)
; #define LAS __attribute__((address_space(3)))
; __device__ __forceinline__ unsigned pk2(float lo, float hi) { return f2bf(lo) | (f2bf(hi) << 16); }
; __device__ __forceinline__ float bflo(unsigned w) { return __uint_as_float(w << 16); }
; __device__ __forceinline__ float bfhi(unsigned w) { return __uint_as_float(w & 0xffff0000u); }
; __device__ __forceinline__ void sgu_item(LAS unsigned char* wl, const bf16* proj, bf16* ymix, const float* vstat, const float* sgu_g, const bf16* Wm, const float* sgu_b, int chunk, int h, int lane) {
;     ...
;         for (int i = 0; i < 8; ++i) { const int s = rsub + 16 * i; const f32x2 ms = st[s]; const v4u w = raw[i];
;             v2u lo, hi; lo.x = pk2((bflo(w.x) - ms.x) * ms.y * g0[0], (bfhi(w.x) - ms.x) * ms.y * g0[1]); lo.y = pk2((bflo(w.y) - ms.x) * ms.y * g0[2], (bfhi(w.y) - ms.x) * ms.y * g0[3]);
;             hi.x = pk2((bflo(w.z) - ms.x) * ms.y * g1[0], (bfhi(w.z) - ms.x) * ms.y * g1[1]); hi.y = pk2((bflo(w.w) - ms.x) * ms.y * g1[2], (bfhi(w.w) - ms.x) * ms.y * g1[3]);
;             *(LAS v2u*)(wl + s * VP2 + (4 * c16) * 2) = lo; *(LAS v2u*)(wl + s * VP2 + (16 + 4 * c16) * 2) = hi; }
	v_pk_add_f32 v[108:109], v[108:109], v[88:89] op_sel_hi:[1,0] neg_lo:[0,1] neg_hi:[0,1]
	v_pk_add_f32 v[104:105], v[104:105], v[88:89] op_sel_hi:[1,0] neg_lo:[0,1] neg_hi:[0,1]
	v_pk_mul_f32 v[108:109], v[88:89], v[108:109] op_sel:[1,0]
	v_pk_mul_f32 v[104:105], v[88:89], v[104:105] op_sel:[1,0]
	v_pk_mul_f32 v[108:109], v[116:117], v[108:109]
	v_pk_mul_f32 v[104:105], v[94:95], v[104:105]
	v_and_b32_sdwa v111, v109, v245 dst_sel:DWORD dst_unused:UNUSED_PAD src0_sel:WORD_1 src1_sel:DWORD
	v_and_b32_sdwa v112, v108, v245 dst_sel:DWORD dst_unused:UNUSED_PAD src0_sel:WORD_1 src1_sel:DWORD
	v_add3_u32 v108, v108, v112, s68
	v_add3_u32 v109, v109, v111, s68
	v_and_b32_sdwa v111, v105, v245 dst_sel:DWORD dst_unused:UNUSED_PAD src0_sel:WORD_1 src1_sel:DWORD
	v_and_b32_sdwa v112, v104, v245 dst_sel:DWORD dst_unused:UNUSED_PAD src0_sel:WORD_1 src1_sel:DWORD
	v_add3_u32 v105, v105, v111, s68
	v_add3_u32 v104, v104, v112, s68
	v_and_b32_e32 v105, 0xffff0000, v105
	v_and_b32_e32 v104, 0xffff0000, v104
	v_or_b32_sdwa v105, v105, v109 dst_sel:DWORD dst_unused:UNUSED_PAD src0_sel:DWORD src1_sel:WORD_1
	v_or_b32_sdwa v104, v104, v108 dst_sel:DWORD dst_unused:UNUSED_PAD src0_sel:DWORD src1_sel:WORD_1
	v_lshlrev_b32_e32 v109, 16, v107
	v_lshlrev_b32_e32 v108, 16, v106
	v_pk_add_f32 v[108:109], v[108:109], v[88:89] op_sel_hi:[1,0] neg_lo:[0,1] neg_hi:[0,1]
	v_and_b32_e32 v107, 0xffff0000, v107
	v_and_b32_e32 v106, 0xffff0000, v106
	v_pk_mul_f32 v[108:109], v[88:89], v[108:109] op_sel:[1,0]
	v_pk_add_f32 v[106:107], v[106:107], v[88:89] op_sel_hi:[1,0] neg_lo:[0,1] neg_hi:[0,1]
	v_pk_mul_f32 v[108:109], v[92:93], v[108:109]
	v_pk_mul_f32 v[88:89], v[88:89], v[106:107] op_sel:[1,0]
	v_and_b32_sdwa v106, v109, v245 dst_sel:DWORD dst_unused:UNUSED_PAD src0_sel:WORD_1 src1_sel:DWORD
	v_pk_mul_f32 v[88:89], v[90:91], v[88:89]
	v_and_b32_sdwa v107, v108, v245 dst_sel:DWORD dst_unused:UNUSED_PAD src0_sel:WORD_1 src1_sel:DWORD
	v_add3_u32 v107, v108, v107, s68
	v_add3_u32 v106, v109, v106, s68
	v_and_b32_sdwa v108, v89, v245 dst_sel:DWORD dst_unused:UNUSED_PAD src0_sel:WORD_1 src1_sel:DWORD
	v_and_b32_sdwa v109, v88, v245 dst_sel:DWORD dst_unused:UNUSED_PAD src0_sel:WORD_1 src1_sel:DWORD
	v_add3_u32 v89, v89, v108, s68
	v_add3_u32 v88, v88, v109, s68
	v_and_b32_e32 v89, 0xffff0000, v89
	v_and_b32_e32 v88, 0xffff0000, v88
	v_or_b32_sdwa v89, v89, v106 dst_sel:DWORD dst_unused:UNUSED_PAD src0_sel:DWORD src1_sel:WORD_1
	v_or_b32_sdwa v88, v88, v107 dst_sel:DWORD dst_unused:UNUSED_PAD src0_sel:DWORD src1_sel:WORD_1
	ds_write2_b64 v110, v[104:105], v[88:89] offset0:224 offset1:228
	ds_read_b64 v[104:105], v218 offset:10752
	v_lshlrev_b32_e32 v89, 16, v101
	v_lshlrev_b32_e32 v88, 16, v100
	v_and_b32_e32 v101, 0xffff0000, v101
	v_and_b32_e32 v100, 0xffff0000, v100
	s_waitcnt lgkmcnt(0)
	v_pk_add_f32 v[88:89], v[88:89], v[104:105] op_sel_hi:[1,0] neg_lo:[0,1] neg_hi:[0,1]
	v_pk_add_f32 v[100:101], v[100:101], v[104:105] op_sel_hi:[1,0] neg_lo:[0,1] neg_hi:[0,1]
	v_pk_mul_f32 v[88:89], v[104:105], v[88:89] op_sel:[1,0]
	v_pk_mul_f32 v[100:101], v[104:105], v[100:101] op_sel:[1,0]
	v_pk_mul_f32 v[88:89], v[116:117], v[88:89]
	v_pk_mul_f32 v[100:101], v[94:95], v[100:101]
	v_and_b32_sdwa v106, v89, v245 dst_sel:DWORD dst_unused:UNUSED_PAD src0_sel:WORD_1 src1_sel:DWORD
	v_and_b32_sdwa v107, v88, v245 dst_sel:DWORD dst_unused:UNUSED_PAD src0_sel:WORD_1 src1_sel:DWORD
	v_add3_u32 v88, v88, v107, s68
	v_add3_u32 v89, v89, v106, s68
	v_and_b32_sdwa v106, v101, v245 dst_sel:DWORD dst_unused:UNUSED_PAD src0_sel:WORD_1 src1_sel:DWORD
	v_and_b32_sdwa v107, v100, v245 dst_sel:DWORD dst_unused:UNUSED_PAD src0_sel:WORD_1 src1_sel:DWORD
	v_add3_u32 v101, v101, v106, s68
	v_add3_u32 v100, v100, v107, s68
	v_and_b32_e32 v101, 0xffff0000, v101
	v_and_b32_e32 v100, 0xffff0000, v100
	v_or_b32_sdwa v89, v101, v89 dst_sel:DWORD dst_unused:UNUSED_PAD src0_sel:DWORD src1_sel:WORD_1
	v_or_b32_sdwa v88, v100, v88 dst_sel:DWORD dst_unused:UNUSED_PAD src0_sel:DWORD src1_sel:WORD_1
	v_lshlrev_b32_e32 v101, 16, v103
	v_lshlrev_b32_e32 v100, 16, v102
	v_pk_add_f32 v[100:101], v[100:101], v[104:105] op_sel_hi:[1,0] neg_lo:[0,1] neg_hi:[0,1]
	v_and_b32_e32 v103, 0xffff0000, v103
	v_and_b32_e32 v102, 0xffff0000, v102
	v_pk_mul_f32 v[100:101], v[104:105], v[100:101] op_sel:[1,0]
	v_pk_add_f32 v[102:103], v[102:103], v[104:105] op_sel_hi:[1,0] neg_lo:[0,1] neg_hi:[0,1]
	v_pk_mul_f32 v[100:101], v[92:93], v[100:101]
	v_pk_mul_f32 v[102:103], v[104:105], v[102:103] op_sel:[1,0]
	v_and_b32_sdwa v104, v101, v245 dst_sel:DWORD dst_unused:UNUSED_PAD src0_sel:WORD_1 src1_sel:DWORD
	v_pk_mul_f32 v[102:103], v[90:91], v[102:103]
	v_and_b32_sdwa v105, v100, v245 dst_sel:DWORD dst_unused:UNUSED_PAD src0_sel:WORD_1 src1_sel:DWORD
	v_add3_u32 v100, v100, v105, s68
	v_add3_u32 v101, v101, v104, s68
	v_and_b32_sdwa v104, v103, v245 dst_sel:DWORD dst_unused:UNUSED_PAD src0_sel:WORD_1 src1_sel:DWORD
	v_and_b32_sdwa v105, v102, v245 dst_sel:DWORD dst_unused:UNUSED_PAD src0_sel:WORD_1 src1_sel:DWORD
	v_add3_u32 v103, v103, v104, s68
	v_add3_u32 v102, v102, v105, s68
	v_and_b32_e32 v103, 0xffff0000, v103
	v_and_b32_e32 v102, 0xffff0000, v102
	v_or_b32_sdwa v101, v103, v101 dst_sel:DWORD dst_unused:UNUSED_PAD src0_sel:DWORD src1_sel:WORD_1
	v_or_b32_sdwa v100, v102, v100 dst_sel:DWORD dst_unused:UNUSED_PAD src0_sel:DWORD src1_sel:WORD_1
	v_add_u32_e32 v102, 0x1000, v219
	ds_write2_b64 v102, v[88:89], v[100:101] offset0:128 offset1:132
	ds_read_b64 v[88:89], v218 offset:10880
	v_lshlrev_b32_e32 v101, 16, v97
	v_lshlrev_b32_e32 v100, 16, v96
	v_and_b32_e32 v97, 0xffff0000, v97
	v_and_b32_e32 v96, 0xffff0000, v96
	s_waitcnt lgkmcnt(0)
; #define LAS __attribute__((address_space(3)))
; __device__ __forceinline__ unsigned pk2(float lo, float hi) { return f2bf(lo) | (f2bf(hi) << 16); }
; __device__ __forceinline__ float bflo(unsigned w) { return __uint_as_float(w << 16); }
; __device__ __forceinline__ float bfhi(unsigned w) { return __uint_as_float(w & 0xffff0000u); }
; __device__ __forceinline__ void sgu_item(LAS unsigned char* wl, const bf16* proj, bf16* ymix, const float* vstat, const float* sgu_g, const bf16* Wm, const float* sgu_b, int chunk, int h, int lane) {
;     ...
;         for (int i = 0; i < 8; ++i) { const int s = rsub + 16 * i; const f32x2 ms = st[s]; const v4u w = raw[i];
;             v2u lo, hi; lo.x = pk2((bflo(w.x) - ms.x) * ms.y * g0[0], (bfhi(w.x) - ms.x) * ms.y * g0[1]); lo.y = pk2((bflo(w.y) - ms.x) * ms.y * g0[2], (bfhi(w.y) - ms.x) * ms.y * g0[3]);
;             hi.x = pk2((bflo(w.z) - ms.x) * ms.y * g1[0], (bfhi(w.z) - ms.x) * ms.y * g1[1]); hi.y = pk2((bflo(w.w) - ms.x) * ms.y * g1[2], (bfhi(w.w) - ms.x) * ms.y * g1[3]);
;             *(LAS v2u*)(wl + s * VP2 + (4 * c16) * 2) = lo; *(LAS v2u*)(wl + s * VP2 + (16 + 4 * c16) * 2) = hi; }
	v_pk_add_f32 v[100:101], v[100:101], v[88:89] op_sel_hi:[1,0] neg_lo:[0,1] neg_hi:[0,1]
	v_pk_add_f32 v[96:97], v[96:97], v[88:89] op_sel_hi:[1,0] neg_lo:[0,1] neg_hi:[0,1]
	v_pk_mul_f32 v[100:101], v[88:89], v[100:101] op_sel:[1,0]
	v_pk_mul_f32 v[96:97], v[88:89], v[96:97] op_sel:[1,0]
	v_pk_mul_f32 v[100:101], v[116:117], v[100:101]
	v_pk_mul_f32 v[96:97], v[94:95], v[96:97]
	v_and_b32_sdwa v102, v101, v245 dst_sel:DWORD dst_unused:UNUSED_PAD src0_sel:WORD_1 src1_sel:DWORD
	v_and_b32_sdwa v103, v100, v245 dst_sel:DWORD dst_unused:UNUSED_PAD src0_sel:WORD_1 src1_sel:DWORD
	v_add3_u32 v100, v100, v103, s68
	v_add3_u32 v101, v101, v102, s68
	v_and_b32_sdwa v102, v97, v245 dst_sel:DWORD dst_unused:UNUSED_PAD src0_sel:WORD_1 src1_sel:DWORD
	v_and_b32_sdwa v103, v96, v245 dst_sel:DWORD dst_unused:UNUSED_PAD src0_sel:WORD_1 src1_sel:DWORD
	v_add3_u32 v97, v97, v102, s68
	v_add3_u32 v96, v96, v103, s68
	v_and_b32_e32 v97, 0xffff0000, v97
	v_and_b32_e32 v96, 0xffff0000, v96
	v_or_b32_sdwa v97, v97, v101 dst_sel:DWORD dst_unused:UNUSED_PAD src0_sel:DWORD src1_sel:WORD_1
	v_or_b32_sdwa v96, v96, v100 dst_sel:DWORD dst_unused:UNUSED_PAD src0_sel:DWORD src1_sel:WORD_1
	v_lshlrev_b32_e32 v101, 16, v99
	v_lshlrev_b32_e32 v100, 16, v98
	v_pk_add_f32 v[100:101], v[100:101], v[88:89] op_sel_hi:[1,0] neg_lo:[0,1] neg_hi:[0,1]
	v_and_b32_e32 v99, 0xffff0000, v99
	v_and_b32_e32 v98, 0xffff0000, v98
	v_pk_mul_f32 v[100:101], v[88:89], v[100:101] op_sel:[1,0]
	v_pk_add_f32 v[98:99], v[98:99], v[88:89] op_sel_hi:[1,0] neg_lo:[0,1] neg_hi:[0,1]
	v_pk_mul_f32 v[100:101], v[92:93], v[100:101]
	v_pk_mul_f32 v[88:89], v[88:89], v[98:99] op_sel:[1,0]
	v_and_b32_sdwa v98, v101, v245 dst_sel:DWORD dst_unused:UNUSED_PAD src0_sel:WORD_1 src1_sel:DWORD
	v_pk_mul_f32 v[88:89], v[90:91], v[88:89]
	v_and_b32_sdwa v99, v100, v245 dst_sel:DWORD dst_unused:UNUSED_PAD src0_sel:WORD_1 src1_sel:DWORD
	v_add3_u32 v99, v100, v99, s68
	v_add3_u32 v98, v101, v98, s68
	v_and_b32_sdwa v100, v89, v245 dst_sel:DWORD dst_unused:UNUSED_PAD src0_sel:WORD_1 src1_sel:DWORD
	v_and_b32_sdwa v101, v88, v245 dst_sel:DWORD dst_unused:UNUSED_PAD src0_sel:WORD_1 src1_sel:DWORD
	v_add3_u32 v89, v89, v100, s68
	v_add3_u32 v88, v88, v101, s68
	v_and_b32_e32 v89, 0xffff0000, v89
	v_and_b32_e32 v88, 0xffff0000, v88
	v_or_b32_sdwa v89, v89, v98 dst_sel:DWORD dst_unused:UNUSED_PAD src0_sel:DWORD src1_sel:WORD_1
	v_or_b32_sdwa v88, v88, v99 dst_sel:DWORD dst_unused:UNUSED_PAD src0_sel:DWORD src1_sel:WORD_1
	v_add_u32_e32 v98, 0x1800, v219
	ds_write2_b64 v98, v[96:97], v[88:89] offset0:32 offset1:36
	ds_read_b64 v[88:89], v218 offset:11008
	v_lshlrev_b32_e32 v97, 16, v85
	v_lshlrev_b32_e32 v96, 16, v84
	v_and_b32_e32 v85, 0xffff0000, v85
	v_and_b32_e32 v84, 0xffff0000, v84
	s_waitcnt lgkmcnt(0)
	v_pk_add_f32 v[96:97], v[96:97], v[88:89] op_sel_hi:[1,0] neg_lo:[0,1] neg_hi:[0,1]
	v_pk_add_f32 v[84:85], v[84:85], v[88:89] op_sel_hi:[1,0] neg_lo:[0,1] neg_hi:[0,1]
	v_pk_mul_f32 v[96:97], v[88:89], v[96:97] op_sel:[1,0]
	v_pk_mul_f32 v[84:85], v[88:89], v[84:85] op_sel:[1,0]
	v_pk_mul_f32 v[96:97], v[116:117], v[96:97]
	v_pk_mul_f32 v[84:85], v[94:95], v[84:85]
	v_and_b32_sdwa v99, v97, v245 dst_sel:DWORD dst_unused:UNUSED_PAD src0_sel:WORD_1 src1_sel:DWORD
	v_and_b32_sdwa v100, v96, v245 dst_sel:DWORD dst_unused:UNUSED_PAD src0_sel:WORD_1 src1_sel:DWORD
	v_add3_u32 v96, v96, v100, s68
	v_add3_u32 v97, v97, v99, s68
	v_and_b32_sdwa v99, v85, v245 dst_sel:DWORD dst_unused:UNUSED_PAD src0_sel:WORD_1 src1_sel:DWORD
	v_and_b32_sdwa v100, v84, v245 dst_sel:DWORD dst_unused:UNUSED_PAD src0_sel:WORD_1 src1_sel:DWORD
	v_add3_u32 v85, v85, v99, s68
	v_add3_u32 v84, v84, v100, s68
	v_and_b32_e32 v85, 0xffff0000, v85
	v_and_b32_e32 v84, 0xffff0000, v84
	v_or_b32_sdwa v85, v85, v97 dst_sel:DWORD dst_unused:UNUSED_PAD src0_sel:DWORD src1_sel:WORD_1
	v_or_b32_sdwa v84, v84, v96 dst_sel:DWORD dst_unused:UNUSED_PAD src0_sel:DWORD src1_sel:WORD_1
	v_lshlrev_b32_e32 v97, 16, v87
	v_lshlrev_b32_e32 v96, 16, v86
	v_pk_add_f32 v[96:97], v[96:97], v[88:89] op_sel_hi:[1,0] neg_lo:[0,1] neg_hi:[0,1]
	v_and_b32_e32 v87, 0xffff0000, v87
	v_and_b32_e32 v86, 0xffff0000, v86
	v_pk_mul_f32 v[96:97], v[88:89], v[96:97] op_sel:[1,0]
	v_pk_add_f32 v[86:87], v[86:87], v[88:89] op_sel_hi:[1,0] neg_lo:[0,1] neg_hi:[0,1]
	v_pk_mul_f32 v[96:97], v[92:93], v[96:97]
	v_pk_mul_f32 v[86:87], v[88:89], v[86:87] op_sel:[1,0]
	v_and_b32_sdwa v88, v97, v245 dst_sel:DWORD dst_unused:UNUSED_PAD src0_sel:WORD_1 src1_sel:DWORD
	v_pk_mul_f32 v[86:87], v[90:91], v[86:87]
	v_and_b32_sdwa v89, v96, v245 dst_sel:DWORD dst_unused:UNUSED_PAD src0_sel:WORD_1 src1_sel:DWORD
	v_add3_u32 v89, v96, v89, s68
	v_add3_u32 v88, v97, v88, s68
	v_and_b32_sdwa v96, v87, v245 dst_sel:DWORD dst_unused:UNUSED_PAD src0_sel:WORD_1 src1_sel:DWORD
	v_and_b32_sdwa v97, v86, v245 dst_sel:DWORD dst_unused:UNUSED_PAD src0_sel:WORD_1 src1_sel:DWORD
	v_add3_u32 v87, v87, v96, s68
	v_add3_u32 v86, v86, v97, s68
	v_and_b32_e32 v87, 0xffff0000, v87
	v_and_b32_e32 v86, 0xffff0000, v86
	v_or_b32_sdwa v87, v87, v88 dst_sel:DWORD dst_unused:UNUSED_PAD src0_sel:DWORD src1_sel:WORD_1
	v_or_b32_sdwa v86, v86, v89 dst_sel:DWORD dst_unused:UNUSED_PAD src0_sel:DWORD src1_sel:WORD_1
	ds_write2_b64 v98, v[84:85], v[86:87] offset0:192 offset1:196
	ds_read_b64 v[84:85], v218 offset:11136
	v_lshlrev_b32_e32 v87, 16, v81
	v_lshlrev_b32_e32 v86, 16, v80
	v_and_b32_e32 v81, 0xffff0000, v81
	v_and_b32_e32 v80, 0xffff0000, v80
	s_waitcnt lgkmcnt(0)
; #define LAS __attribute__((address_space(3)))
; #define MFMA16(a, b, c) __builtin_amdgcn_mfma_f32_16x16x32_bf16((a), (b), (c), 0, 0, 0)
; #define LDS_WAIT() asm volatile("s_waitcnt lgkmcnt(0)" ::: "memory")
; __device__ __forceinline__ void sgu_item(LAS unsigned char* wl, const bf16* proj, bf16* ymix, const float* vstat, const float* sgu_g, const bf16* Wm, const float* sgu_b, int chunk, int h, int lane) {
;     ...
;             *(LAS v2u*)(wl + s * VP2 + (4 * c16) * 2) = lo; *(LAS v2u*)(wl + s * VP2 + (16 + 4 * c16) * 2) = hi; }
;         v4u uu8[8];
; #pragma unroll
;         for (int tb = 0; tb < 8; ++tb) uu8[tb] = __builtin_nontemporal_load((const v4u*)(proj + (R0 + 16 * tb + r) * DIN + 512 + colv + 8 * q));
;         LDS_WAIT();
;         v2u olo[8];
; #pragma unroll
;         for (int n = 0; n < 2; ++n) {
;             f32x4 z[8];
; #pragma unroll
;             for (int tb = 0; tb < 8; ++tb) z[tb] = (f32x4){0.f, 0.f, 0.f, 0.f};
;             int f = 0;
; #pragma unroll
;             for (int ks = 0; ks < 4; ++ks) {
;                 LAS unsigned char* ad = wl + (ks * 32 + 8 * q + (r >> 2)) * VP2 + (16 * n) * 2 + 8 * (r & 3);
;                 const s16x4 lo = __builtin_bit_cast(s16x4, __builtin_amdgcn_ds_read_tr16_b64_v4i16((LAS s16x4*)ad));
;                 const s16x4 hi = __builtin_bit_cast(s16x4, __builtin_amdgcn_ds_read_tr16_b64_v4i16((LAS s16x4*)(ad + 4 * VP2)));
;                 const bf16x8 vf = __builtin_shufflevector(lo, hi, 0, 1, 2, 3, 4, 5, 6, 7);
; #pragma unroll
;                 for (int tb = 2 * ks; tb < 8; ++tb) z[tb] = MFMA16(vf, wmf[f++], z[tb]);
	v_pk_add_f32 v[86:87], v[86:87], v[84:85] op_sel_hi:[1,0] neg_lo:[0,1] neg_hi:[0,1]
	v_pk_add_f32 v[80:81], v[80:81], v[84:85] op_sel_hi:[1,0] neg_lo:[0,1] neg_hi:[0,1]
	v_pk_mul_f32 v[86:87], v[84:85], v[86:87] op_sel:[1,0]
	v_pk_mul_f32 v[80:81], v[84:85], v[80:81] op_sel:[1,0]
	v_pk_mul_f32 v[86:87], v[116:117], v[86:87]
	v_pk_mul_f32 v[80:81], v[94:95], v[80:81]
	v_and_b32_sdwa v88, v87, v245 dst_sel:DWORD dst_unused:UNUSED_PAD src0_sel:WORD_1 src1_sel:DWORD
	v_and_b32_sdwa v89, v86, v245 dst_sel:DWORD dst_unused:UNUSED_PAD src0_sel:WORD_1 src1_sel:DWORD
	v_add3_u32 v86, v86, v89, s68
	v_add3_u32 v87, v87, v88, s68
	v_and_b32_sdwa v88, v81, v245 dst_sel:DWORD dst_unused:UNUSED_PAD src0_sel:WORD_1 src1_sel:DWORD
	v_and_b32_sdwa v89, v80, v245 dst_sel:DWORD dst_unused:UNUSED_PAD src0_sel:WORD_1 src1_sel:DWORD
	v_add3_u32 v81, v81, v88, s68
	v_add3_u32 v80, v80, v89, s68
	v_and_b32_e32 v81, 0xffff0000, v81
	v_and_b32_e32 v80, 0xffff0000, v80
	v_or_b32_sdwa v81, v81, v87 dst_sel:DWORD dst_unused:UNUSED_PAD src0_sel:DWORD src1_sel:WORD_1
	v_or_b32_sdwa v80, v80, v86 dst_sel:DWORD dst_unused:UNUSED_PAD src0_sel:DWORD src1_sel:WORD_1
	v_lshlrev_b32_e32 v87, 16, v83
	v_lshlrev_b32_e32 v86, 16, v82
	v_pk_add_f32 v[86:87], v[86:87], v[84:85] op_sel_hi:[1,0] neg_lo:[0,1] neg_hi:[0,1]
	v_and_b32_e32 v83, 0xffff0000, v83
	v_and_b32_e32 v82, 0xffff0000, v82
	v_pk_mul_f32 v[86:87], v[84:85], v[86:87] op_sel:[1,0]
	v_pk_add_f32 v[82:83], v[82:83], v[84:85] op_sel_hi:[1,0] neg_lo:[0,1] neg_hi:[0,1]
	v_pk_mul_f32 v[86:87], v[92:93], v[86:87]
	v_pk_mul_f32 v[82:83], v[84:85], v[82:83] op_sel:[1,0]
	v_and_b32_sdwa v84, v87, v245 dst_sel:DWORD dst_unused:UNUSED_PAD src0_sel:WORD_1 src1_sel:DWORD
	v_pk_mul_f32 v[82:83], v[90:91], v[82:83]
	v_and_b32_sdwa v85, v86, v245 dst_sel:DWORD dst_unused:UNUSED_PAD src0_sel:WORD_1 src1_sel:DWORD
	v_add3_u32 v85, v86, v85, s68
	v_add3_u32 v84, v87, v84, s68
	v_and_b32_sdwa v86, v83, v245 dst_sel:DWORD dst_unused:UNUSED_PAD src0_sel:WORD_1 src1_sel:DWORD
	v_and_b32_sdwa v87, v82, v245 dst_sel:DWORD dst_unused:UNUSED_PAD src0_sel:WORD_1 src1_sel:DWORD
	v_add3_u32 v83, v83, v86, s68
	v_add3_u32 v82, v82, v87, s68
	v_and_b32_e32 v83, 0xffff0000, v83
	v_and_b32_e32 v82, 0xffff0000, v82
	v_or_b32_sdwa v83, v83, v84 dst_sel:DWORD dst_unused:UNUSED_PAD src0_sel:DWORD src1_sel:WORD_1
	v_or_b32_sdwa v82, v82, v85 dst_sel:DWORD dst_unused:UNUSED_PAD src0_sel:DWORD src1_sel:WORD_1
	v_add_u32_e32 v84, 0x2000, v219
	ds_write2_b64 v84, v[80:81], v[82:83] offset0:96 offset1:100
	v_lshl_add_u64 v[80:81], v[188:189], 0, s[20:21]
	v_add_co_u32_e32 v82, vcc, s0, v80
	s_mov_b32 s0, 0xf10c000
	s_nop 0
	v_addc_co_u32_e32 v83, vcc, 0, v81, vcc
	global_load_dwordx4 v[104:107], v[82:83], off offset:1024 nt
	v_add_co_u32_e32 v82, vcc, s0, v80
	s_mov_b32 s0, 0xf118000
	s_nop 0
	v_addc_co_u32_e32 v83, vcc, 0, v81, vcc
	global_load_dwordx4 v[100:103], v[82:83], off offset:1024 nt
	v_add_co_u32_e32 v82, vcc, s0, v80
	s_mov_b32 s0, 0xf130000
	s_nop 0
	v_addc_co_u32_e32 v83, vcc, 0, v81, vcc
	global_load_dwordx4 v[96:99], v[82:83], off offset:1024 nt
	v_lshl_add_u64 v[82:83], v[190:191], 0, s[20:21]
	global_load_dwordx4 v[92:95], v[82:83], off nt
	v_add_co_u32_e32 v82, vcc, s0, v80
	s_mov_b32 s0, 0xf13c000
	s_nop 0
	v_addc_co_u32_e32 v83, vcc, 0, v81, vcc
	global_load_dwordx4 v[88:91], v[82:83], off offset:1024 nt
	v_add_co_u32_e32 v82, vcc, s0, v80
	s_mov_b32 s0, 0xf148000
	s_nop 0
	v_addc_co_u32_e32 v83, vcc, 0, v81, vcc
	global_load_dwordx4 v[84:87], v[82:83], off offset:1024 nt
	v_add_co_u32_e32 v80, vcc, s0, v80
	v_lshl_add_u64 v[108:109], v[186:187], 0, s[20:21]
	s_nop 0
	v_addc_co_u32_e32 v81, vcc, 0, v81, vcc
	global_load_dwordx4 v[80:83], v[80:81], off offset:1024 nt
	s_mov_b32 s0, 0x10900000
	global_load_dwordx4 v[108:111], v[108:109], off nt
	s_waitcnt lgkmcnt(0)
	ds_read_b64_tr_b16 v[116:117], v220 offset:320
	ds_read_b64_tr_b16 v[114:115], v220
	ds_read_b64_tr_b16 v[112:113], v220 offset:32
	ds_read_b64_tr_b16 v[208:209], v220 offset:2560
	ds_read_b64_tr_b16 v[210:211], v220 offset:2880
	s_waitcnt lgkmcnt(0)
	v_mfma_f32_16x16x32_bf16 v[118:121], v[114:117], v[0:3], 0
	v_mfma_f32_16x16x32_bf16 v[122:125], v[114:117], v[4:7], 0
	s_nop 6
	v_mov_b32_e32 v138, v119
	v_mov_b32_e32 v119, v120
	v_pk_add_f32 v[118:119], v[162:163], v[118:119]
	v_mfma_f32_16x16x32_bf16 v[126:129], v[114:117], v[8:11], 0
	v_mov_b32_e32 v139, v121
	v_pk_add_f32 v[138:139], v[162:163], v[138:139]
	v_mfma_f32_16x16x32_bf16 v[130:133], v[114:117], v[16:19], 0
	v_mfma_f32_16x16x32_bf16 v[134:137], v[114:117], v[24:27], 0
	v_mfma_f32_16x16x32_bf16 v[200:203], v[114:117], v[48:51], 0
	v_mfma_f32_16x16x32_bf16 v[204:207], v[114:117], v[32:35], 0
	v_mfma_f32_16x16x32_bf16 v[114:117], v[114:117], v[40:43], 0
	v_mfma_f32_16x16x32_bf16 v[126:129], v[208:211], v[12:15], v[126:129]
	v_mfma_f32_16x16x32_bf16 v[130:133], v[208:211], v[20:23], v[130:133]
	v_mfma_f32_16x16x32_bf16 v[134:137], v[208:211], v[28:31], v[134:137]
	v_mfma_f32_16x16x32_bf16 v[200:203], v[208:211], v[56:59], v[200:203]
	v_mfma_f32_16x16x32_bf16 v[204:207], v[208:211], v[36:39], v[204:207]
	v_mfma_f32_16x16x32_bf16 v[114:117], v[208:211], v[44:47], v[114:117]
	ds_read_b64_tr_b16 v[208:209], v220 offset:5120
	ds_read_b64_tr_b16 v[210:211], v220 offset:5440
	s_waitcnt lgkmcnt(0)
	v_mfma_f32_16x16x32_bf16 v[222:225], v[208:211], v[60:63], v[200:203]
	v_mfma_f32_16x16x32_bf16 v[200:203], v[208:211], v[64:67], v[204:207]
	s_nop 2
	ds_read_b64_tr_b16 v[204:205], v220 offset:7680
	ds_read_b64_tr_b16 v[206:207], v220 offset:8000
	s_waitcnt lgkmcnt(0)
	v_mfma_f32_16x16x32_bf16 v[226:229], v[204:207], v[68:71], v[200:203]
	s_waitcnt vmcnt(0)
; #define MFMA16(a, b, c) __builtin_amdgcn_mfma_f32_16x16x32_bf16((a), (b), (c), 0, 0, 0)
; __device__ __forceinline__ unsigned pk2(float lo, float hi) { return f2bf(lo) | (f2bf(hi) << 16); }
; __device__ __forceinline__ float bflo(unsigned w) { return __uint_as_float(w << 16); }
; __device__ __forceinline__ float bfhi(unsigned w) { return __uint_as_float(w & 0xffff0000u); }
; __device__ __forceinline__ void sgu_item(LAS unsigned char* wl, const bf16* proj, bf16* ymix, const float* vstat, const float* sgu_g, const bf16* Wm, const float* sgu_b, int chunk, int h, int lane) {
;     ...
;                 for (int tb = 2 * ks; tb < 8; ++tb) z[tb] = MFMA16(vf, wmf[f++], z[tb]);
;             }
; #pragma unroll
;             for (int tb = 0; tb < 8; ++tb) { const v4u uu = uu8[tb]; const unsigned ux = n == 0 ? uu.x : uu.z, uy = n == 0 ? uu.y : uu.w;
;                 v2u o; o.x = pk2(bflo(ux) * (z[tb][0] + bias[tb]), bfhi(ux) * (z[tb][1] + bias[tb])); o.y = pk2(bflo(uy) * (z[tb][2] + bias[tb]), bfhi(uy) * (z[tb][3] + bias[tb]));
;                 if (n == 0) olo[tb] = o;
;                 else { v4u w; w.x = olo[tb].x; w.y = olo[tb].y; w.z = o.x; w.w = o.y; *(v4u*)(ymix + (R0 + 16 * tb + r) * D + 512 + colv + 8 * q) = w; } }
	s_nop 1
	v_and_b32_e32 v201, 0xffff0000, v105
	v_and_b32_e32 v200, 0xffff0000, v104
	v_lshlrev_b32_e32 v105, 16, v105
	v_lshlrev_b32_e32 v104, 16, v104
	v_pk_mul_f32 v[214:215], v[118:119], v[104:105]
	v_mov_b32_e32 v104, v123
	v_mov_b32_e32 v105, v125
	v_pk_add_f32 v[104:105], v[164:165], v[104:105]
	v_and_b32_e32 v119, 0xffff0000, v101
	v_and_b32_e32 v118, 0xffff0000, v100
	v_mov_b32_e32 v123, v124
	v_mfma_f32_16x16x32_bf16 v[114:117], v[208:211], v[72:75], v[114:117]
	v_mul_f32_e64 v212, v104, v118
	v_mul_f32_e64 v213, v105, v119
	v_pk_add_f32 v[104:105], v[164:165], v[122:123]
	v_lshlrev_b32_e32 v101, 16, v101
	v_lshlrev_b32_e32 v100, 16, v100
	v_mfma_f32_16x16x32_bf16 v[134:137], v[208:211], v[52:55], v[134:137]
	v_mul_f32_e64 v210, v104, v100
	v_mul_f32_e64 v211, v105, v101
	v_mov_b32_e32 v100, v127
	v_mov_b32_e32 v101, v129
	v_pk_add_f32 v[100:101], v[166:167], v[100:101]
	v_and_b32_e32 v105, 0xffff0000, v97
	v_and_b32_e32 v104, 0xffff0000, v96
	v_mov_b32_e32 v127, v128
	v_pk_mul_f32 v[208:209], v[100:101], v[104:105]
	v_pk_add_f32 v[100:101], v[166:167], v[126:127]
	v_lshlrev_b32_e32 v97, 16, v97
	v_lshlrev_b32_e32 v96, 16, v96
	v_mfma_f32_16x16x32_bf16 v[114:117], v[204:207], v[76:79], v[114:117]
	v_mul_f32_e64 v206, v100, v96
	v_mul_f32_e64 v207, v101, v97
	v_mov_b32_e32 v96, v131
	v_mov_b32_e32 v97, v133
	v_pk_add_f32 v[96:97], v[168:169], v[96:97]
	v_and_b32_e32 v101, 0xffff0000, v93
	v_and_b32_e32 v100, 0xffff0000, v92
	v_mov_b32_e32 v131, v132
	v_pk_mul_f32 v[204:205], v[96:97], v[100:101]
	v_pk_add_f32 v[96:97], v[168:169], v[130:131]
	v_lshlrev_b32_e32 v93, 16, v93
	v_lshlrev_b32_e32 v92, 16, v92
	v_pk_mul_f32 v[202:203], v[96:97], v[92:93]
	v_mov_b32_e32 v92, v135
	v_mov_b32_e32 v93, v137
	v_pk_add_f32 v[92:93], v[170:171], v[92:93]
	v_and_b32_e32 v97, 0xffff0000, v89
	v_and_b32_e32 v96, 0xffff0000, v88
	v_mov_b32_e32 v135, v136
	v_pk_mul_f32 v[216:217], v[138:139], v[200:201]
	v_pk_mul_f32 v[200:201], v[92:93], v[96:97]
	v_pk_add_f32 v[92:93], v[170:171], v[134:135]
	v_lshlrev_b32_e32 v89, 16, v89
	v_lshlrev_b32_e32 v88, 16, v88
	v_pk_mul_f32 v[104:105], v[92:93], v[88:89]
	v_mov_b32_e32 v88, v223
	v_mov_b32_e32 v89, v225
	v_pk_add_f32 v[88:89], v[172:173], v[88:89]
	v_and_b32_e32 v93, 0xffff0000, v85
	v_and_b32_e32 v92, 0xffff0000, v84
	v_mov_b32_e32 v223, v224
	v_pk_mul_f32 v[100:101], v[88:89], v[92:93]
	v_pk_add_f32 v[88:89], v[172:173], v[222:223]
	v_lshlrev_b32_e32 v85, 16, v85
	v_lshlrev_b32_e32 v84, 16, v84
	v_pk_mul_f32 v[96:97], v[88:89], v[84:85]
	v_mov_b32_e32 v84, v227
	v_mov_b32_e32 v85, v229
	v_pk_add_f32 v[84:85], v[174:175], v[84:85]
	v_and_b32_e32 v89, 0xffff0000, v81
	v_and_b32_e32 v88, 0xffff0000, v80
	v_mov_b32_e32 v227, v228
	v_pk_mul_f32 v[92:93], v[84:85], v[88:89]
	v_pk_add_f32 v[84:85], v[174:175], v[226:227]
	v_lshlrev_b32_e32 v81, 16, v81
	v_lshlrev_b32_e32 v80, 16, v80
	v_pk_mul_f32 v[80:81], v[84:85], v[80:81]
	v_mov_b32_e32 v84, v115
	v_mov_b32_e32 v85, v117
	v_pk_add_f32 v[84:85], v[176:177], v[84:85]
	v_and_b32_e32 v89, 0xffff0000, v109
	v_and_b32_e32 v88, 0xffff0000, v108
	v_mov_b32_e32 v115, v116
	v_pk_mul_f32 v[88:89], v[84:85], v[88:89]
	v_pk_add_f32 v[84:85], v[176:177], v[114:115]
	ds_read_b64_tr_b16 v[114:115], v220 offset:352
	ds_read_b64_tr_b16 v[234:235], v220 offset:2592
	ds_read_b64_tr_b16 v[236:237], v220 offset:2912
	s_waitcnt lgkmcnt(2)
	v_mfma_f32_16x16x32_bf16 v[120:123], v[112:115], v[16:19], 0
	v_lshlrev_b32_e32 v109, 16, v109
	v_lshlrev_b32_e32 v108, 16, v108
	v_pk_mul_f32 v[84:85], v[84:85], v[108:109]
	v_mfma_f32_16x16x32_bf16 v[226:229], v[112:115], v[48:51], 0
	v_bfe_u32 v196, v216, 16, 1
	v_add3_u32 v196, v216, v196, s68
	v_bfe_u32 v195, v217, 16, 1
	v_mfma_f32_16x16x32_bf16 v[230:233], v[112:115], v[32:35], 0
	v_add3_u32 v195, v217, v195, s68
	v_mfma_f32_16x16x32_bf16 v[116:119], v[112:115], v[8:11], 0
	v_mfma_f32_16x16x32_bf16 v[124:127], v[112:115], v[24:27], 0
	v_mfma_f32_16x16x32_bf16 v[222:225], v[112:115], v[0:3], 0
	v_mfma_f32_16x16x32_bf16 v[132:135], v[112:115], v[4:7], 0
	v_mfma_f32_16x16x32_bf16 v[112:115], v[112:115], v[40:43], 0
	s_nop 5
	v_mov_b32_e32 v108, v223
	v_mov_b32_e32 v223, v224
	v_mov_b32_e32 v109, v225
	s_waitcnt lgkmcnt(0)
	v_mfma_f32_16x16x32_bf16 v[128:131], v[234:237], v[20:23], v[120:123]
	v_add_f32_e64 v222, v162, v222
	v_add_f32_e64 v223, v163, v223
	v_pk_add_f32 v[108:109], v[162:163], v[108:109]
	v_mfma_f32_16x16x32_bf16 v[120:123], v[234:237], v[56:59], v[226:229]
	v_mfma_f32_16x16x32_bf16 v[226:229], v[234:237], v[36:39], v[230:233]
	s_nop 2
	ds_read_b64_tr_b16 v[230:231], v220 offset:5152
	ds_read_b64_tr_b16 v[232:233], v220 offset:5472
	v_mfma_f32_16x16x32_bf16 v[136:139], v[234:237], v[12:15], v[116:119]
	v_mfma_f32_16x16x32_bf16 v[116:119], v[234:237], v[28:31], v[124:127]
	v_mfma_f32_16x16x32_bf16 v[112:115], v[234:237], v[44:47], v[112:115]
	s_waitcnt lgkmcnt(0)
	v_mfma_f32_16x16x32_bf16 v[124:127], v[230:233], v[52:55], v[116:119]
	v_mfma_f32_16x16x32_bf16 v[116:119], v[230:233], v[64:67], v[226:229]
	s_nop 2
	ds_read_b64_tr_b16 v[226:227], v220 offset:7712
	ds_read_b64_tr_b16 v[228:229], v220 offset:8032
	v_mfma_f32_16x16x32_bf16 v[112:115], v[230:233], v[72:75], v[112:115]
	s_waitcnt lgkmcnt(0)
; __device__ __forceinline__ unsigned pk2(float lo, float hi) { return f2bf(lo) | (f2bf(hi) << 16); }
; __device__ __forceinline__ float bflo(unsigned w) { return __uint_as_float(w << 16); }
; __device__ __forceinline__ float bfhi(unsigned w) { return __uint_as_float(w & 0xffff0000u); }
; __device__ __forceinline__ void sgu_item(LAS unsigned char* wl, const bf16* proj, bf16* ymix, const float* vstat, const float* sgu_g, const bf16* Wm, const float* sgu_b, int chunk, int h, int lane) {
;     ...
; #pragma unroll
;             for (int tb = 0; tb < 8; ++tb) { const v4u uu = uu8[tb]; const unsigned ux = n == 0 ? uu.x : uu.z, uy = n == 0 ? uu.y : uu.w;
;                 v2u o; o.x = pk2(bflo(ux) * (z[tb][0] + bias[tb]), bfhi(ux) * (z[tb][1] + bias[tb])); o.y = pk2(bflo(uy) * (z[tb][2] + bias[tb]), bfhi(uy) * (z[tb][3] + bias[tb]));
;                 if (n == 0) olo[tb] = o;
;                 else { v4u w; w.x = olo[tb].x; w.y = olo[tb].y; w.z = o.x; w.w = o.y; *(v4u*)(ymix + (R0 + 16 * tb + r) * D + 512 + colv + 8 * q) = w; } }
	v_mfma_f32_16x16x32_bf16 v[116:119], v[226:229], v[68:71], v[116:119]
	v_mfma_f32_16x16x32_bf16 v[112:115], v[226:229], v[76:79], v[112:115]
	v_and_b32_e32 v227, 0xffff0000, v107
	v_and_b32_e32 v226, 0xffff0000, v106
	v_lshlrev_b32_e32 v107, 16, v107
	v_lshlrev_b32_e32 v106, 16, v106
	v_pk_mul_f32 v[106:107], v[222:223], v[106:107]
	v_pk_mul_f32 v[108:109], v[108:109], v[226:227]
	v_bfe_u32 v197, v106, 16, 1
	v_bfe_u32 v216, v107, 16, 1
	v_bfe_u32 v192, v109, 16, 1
	v_bfe_u32 v194, v108, 16, 1
	v_add3_u32 v107, v107, v216, s68
	v_add3_u32 v106, v106, v197, s68
	v_add3_u32 v108, v108, v194, s68
	v_add3_u32 v109, v109, v192, s68
	v_bfe_u32 v192, v214, 16, 1
	v_bfe_u32 v194, v215, 16, 1
	v_lshrrev_b32_e32 v106, 16, v106
	v_lshrrev_b32_e32 v107, 16, v107
	v_add3_u32 v194, v215, v194, s68
	v_add3_u32 v192, v214, v192, s68
	v_and_or_b32 v217, v109, s37, v107
	v_and_or_b32 v216, v108, s37, v106
	v_lshl_add_u64 v[106:107], v[182:183], 0, s[20:21]
	v_lshrrev_b32_e32 v192, 16, v192
	v_lshrrev_b32_e32 v194, 16, v194
	v_add_co_u32_e32 v108, vcc, s0, v106
	v_and_or_b32 v215, v195, s37, v194
	v_and_or_b32 v214, v196, s37, v192
	v_addc_co_u32_e32 v109, vcc, 0, v107, vcc
	global_store_dwordx4 v[108:109], v[214:217], off offset:1024
	v_mov_b32_e32 v108, v133
	v_mov_b32_e32 v109, v135
	v_mov_b32_e32 v133, v134
	v_pk_add_f32 v[108:109], v[164:165], v[108:109]
	v_and_b32_e32 v215, 0xffff0000, v103
	v_and_b32_e32 v214, 0xffff0000, v102
	v_pk_add_f32 v[132:133], v[164:165], v[132:133]
	v_lshlrev_b32_e32 v103, 16, v103
	v_lshlrev_b32_e32 v102, 16, v102
	v_pk_mul_f32 v[108:109], v[108:109], v[214:215]
	v_pk_mul_f32 v[102:103], v[132:133], v[102:103]
	v_bfe_u32 v134, v213, 16, 1
	v_bfe_u32 v132, v109, 16, 1
	v_bfe_u32 v133, v108, 16, 1
	v_bfe_u32 v135, v212, 16, 1
	v_add3_u32 v194, v213, v134, s68
	v_bfe_u32 v134, v102, 16, 1
	v_add3_u32 v192, v212, v135, s68
	v_add3_u32 v108, v108, v133, s68
	v_add3_u32 v109, v109, v132, s68
	v_bfe_u32 v132, v210, 16, 1
	v_bfe_u32 v133, v211, 16, 1
	v_bfe_u32 v135, v103, 16, 1
	v_add3_u32 v102, v102, v134, s68
	v_add3_u32 v103, v103, v135, s68
	v_add3_u32 v133, v211, v133, s68
	v_add3_u32 v132, v210, v132, s68
	v_lshrrev_b32_e32 v102, 16, v102
	s_mov_b32 s0, 0x10908000
	v_lshrrev_b32_e32 v132, 16, v132
	v_lshrrev_b32_e32 v133, 16, v133
	v_lshrrev_b32_e32 v103, 16, v103
	v_and_or_b32 v134, v108, s37, v102
	v_add_co_u32_e32 v102, vcc, s0, v106
	v_and_or_b32 v135, v109, s37, v103
	v_and_or_b32 v133, v194, s37, v133
	v_and_or_b32 v132, v192, s37, v132
	v_addc_co_u32_e32 v103, vcc, 0, v107, vcc
	global_store_dwordx4 v[102:103], v[132:135], off offset:1024
	v_mov_b32_e32 v102, v137
	v_mov_b32_e32 v103, v139
	v_pk_add_f32 v[102:103], v[166:167], v[102:103]
	v_and_b32_e32 v109, 0xffff0000, v99
	v_and_b32_e32 v108, 0xffff0000, v98
	v_mov_b32_e32 v137, v138
	v_pk_mul_f32 v[102:103], v[102:103], v[108:109]
	v_pk_add_f32 v[108:109], v[166:167], v[136:137]
	v_lshlrev_b32_e32 v99, 16, v99
	v_lshlrev_b32_e32 v98, 16, v98
	v_pk_mul_f32 v[98:99], v[108:109], v[98:99]
	v_bfe_u32 v133, v208, 16, 1
	v_bfe_u32 v108, v103, 16, 1
	v_bfe_u32 v109, v102, 16, 1
	v_add3_u32 v136, v208, v133, s68
	v_bfe_u32 v133, v98, 16, 1
	v_add3_u32 v102, v102, v109, s68
	v_add3_u32 v103, v103, v108, s68
	v_bfe_u32 v108, v206, 16, 1
	v_bfe_u32 v109, v207, 16, 1
	v_bfe_u32 v134, v99, 16, 1
	v_add3_u32 v98, v98, v133, s68
	v_bfe_u32 v132, v209, 16, 1
	v_add3_u32 v99, v99, v134, s68
	v_add3_u32 v109, v207, v109, s68
	v_add3_u32 v108, v206, v108, s68
	v_lshrrev_b32_e32 v98, 16, v98
	s_mov_b32 s0, 0x10910000
	v_add3_u32 v132, v209, v132, s68
	v_lshrrev_b32_e32 v108, 16, v108
	v_lshrrev_b32_e32 v109, 16, v109
	v_lshrrev_b32_e32 v99, 16, v99
	v_and_or_b32 v134, v102, s37, v98
	v_add_co_u32_e32 v98, vcc, s0, v106
	v_and_or_b32 v135, v103, s37, v99
	v_and_or_b32 v133, v132, s37, v109
	v_and_or_b32 v132, v136, s37, v108
	v_addc_co_u32_e32 v99, vcc, 0, v107, vcc
	global_store_dwordx4 v[98:99], v[132:135], off offset:1024
	v_mov_b32_e32 v98, v129
	v_mov_b32_e32 v99, v131
	v_pk_add_f32 v[98:99], v[168:169], v[98:99]
	v_and_b32_e32 v103, 0xffff0000, v95
	v_and_b32_e32 v102, 0xffff0000, v94
	v_mov_b32_e32 v129, v130
	v_pk_mul_f32 v[98:99], v[98:99], v[102:103]
	v_pk_add_f32 v[102:103], v[168:169], v[128:129]
	v_lshlrev_b32_e32 v95, 16, v95
	v_lshlrev_b32_e32 v94, 16, v94
	v_pk_mul_f32 v[94:95], v[102:103], v[94:95]
	v_bfe_u32 v102, v99, 16, 1
	v_bfe_u32 v103, v98, 16, 1
	v_add3_u32 v98, v98, v103, s68
	v_add3_u32 v99, v99, v102, s68
	v_bfe_u32 v102, v202, 16, 1
	v_bfe_u32 v103, v203, 16, 1
	v_bfe_u32 v128, v94, 16, 1
	v_bfe_u32 v129, v95, 16, 1
	v_bfe_u32 v108, v205, 16, 1
	v_bfe_u32 v109, v204, 16, 1
	v_add3_u32 v95, v95, v129, s68
	v_add3_u32 v94, v94, v128, s68
	v_add3_u32 v103, v203, v103, s68
	v_add3_u32 v102, v202, v102, s68
	v_add3_u32 v109, v204, v109, s68
	v_add3_u32 v108, v205, v108, s68
	v_lshrrev_b32_e32 v102, 16, v102
	v_lshrrev_b32_e32 v103, 16, v103
	v_lshrrev_b32_e32 v94, 16, v94
	v_lshrrev_b32_e32 v95, 16, v95
	v_and_or_b32 v131, v99, s37, v95
	v_and_or_b32 v130, v98, s37, v94
	v_and_or_b32 v129, v108, s37, v103
	v_and_or_b32 v128, v109, s37, v102
	v_lshl_add_u64 v[94:95], v[184:185], 0, s[20:21]
	global_store_dwordx4 v[94:95], v[128:131], off
	v_mov_b32_e32 v94, v125
	v_mov_b32_e32 v95, v127
	v_pk_add_f32 v[94:95], v[170:171], v[94:95]
; __device__ __forceinline__ unsigned pk2(float lo, float hi) { return f2bf(lo) | (f2bf(hi) << 16); }
; __device__ __forceinline__ float bflo(unsigned w) { return __uint_as_float(w << 16); }
; __device__ __forceinline__ float bfhi(unsigned w) { return __uint_as_float(w & 0xffff0000u); }
; #define LDS_WAIT() asm volatile("s_waitcnt lgkmcnt(0)" ::: "memory")
; __device__ __forceinline__ void sgu_item(LAS unsigned char* wl, const bf16* proj, bf16* ymix, const float* vstat, const float* sgu_g, const bf16* Wm, const float* sgu_b, int chunk, int h, int lane) {
;     ...
;     for (int dq = 0; dq < 4; ++dq) {
;     ...
;             for (int tb = 0; tb < 8; ++tb) { const v4u uu = uu8[tb]; const unsigned ux = n == 0 ? uu.x : uu.z, uy = n == 0 ? uu.y : uu.w;
;                 v2u o; o.x = pk2(bflo(ux) * (z[tb][0] + bias[tb]), bfhi(ux) * (z[tb][1] + bias[tb])); o.y = pk2(bflo(uy) * (z[tb][2] + bias[tb]), bfhi(uy) * (z[tb][3] + bias[tb]));
;                 if (n == 0) olo[tb] = o;
;                 else { v4u w; w.x = olo[tb].x; w.y = olo[tb].y; w.z = o.x; w.w = o.y; *(v4u*)(ymix + (R0 + 16 * tb + r) * D + 512 + colv + 8 * q) = w; } }
;         }
;         LDS_WAIT();
;     }
	v_and_b32_e32 v99, 0xffff0000, v91
	v_and_b32_e32 v98, 0xffff0000, v90
	v_mov_b32_e32 v125, v126
	v_pk_mul_f32 v[94:95], v[94:95], v[98:99]
	v_pk_add_f32 v[98:99], v[170:171], v[124:125]
	v_lshlrev_b32_e32 v91, 16, v91
	v_lshlrev_b32_e32 v90, 16, v90
	v_pk_mul_f32 v[90:91], v[98:99], v[90:91]
	v_bfe_u32 v103, v200, 16, 1
	v_bfe_u32 v98, v95, 16, 1
	v_bfe_u32 v99, v94, 16, 1
	v_add3_u32 v108, v200, v103, s68
	v_bfe_u32 v103, v90, 16, 1
	v_mfma_f32_16x16x32_bf16 v[120:123], v[230:233], v[60:63], v[120:123]
	v_add3_u32 v94, v94, v99, s68
	v_add3_u32 v95, v95, v98, s68
	v_bfe_u32 v98, v104, 16, 1
	v_bfe_u32 v99, v105, 16, 1
	v_bfe_u32 v109, v91, 16, 1
	v_add3_u32 v90, v90, v103, s68
	v_bfe_u32 v102, v201, 16, 1
	v_add3_u32 v91, v91, v109, s68
	v_add3_u32 v99, v105, v99, s68
	v_add3_u32 v98, v104, v98, s68
	v_lshrrev_b32_e32 v90, 16, v90
	s_mov_b32 s0, 0x10920000
	v_add3_u32 v102, v201, v102, s68
	v_lshrrev_b32_e32 v98, 16, v98
	v_lshrrev_b32_e32 v99, 16, v99
	v_lshrrev_b32_e32 v91, 16, v91
	v_and_or_b32 v104, v94, s37, v90
	v_add_co_u32_e32 v90, vcc, s0, v106
	v_and_or_b32 v105, v95, s37, v91
	v_and_or_b32 v103, v102, s37, v99
	v_and_or_b32 v102, v108, s37, v98
	v_addc_co_u32_e32 v91, vcc, 0, v107, vcc
	global_store_dwordx4 v[90:91], v[102:105], off offset:1024
	v_mov_b32_e32 v90, v121
	v_mov_b32_e32 v91, v123
	v_pk_add_f32 v[90:91], v[172:173], v[90:91]
	v_and_b32_e32 v95, 0xffff0000, v87
	v_and_b32_e32 v94, 0xffff0000, v86
	v_mov_b32_e32 v121, v122
	v_pk_mul_f32 v[90:91], v[90:91], v[94:95]
	v_pk_add_f32 v[94:95], v[172:173], v[120:121]
	v_lshlrev_b32_e32 v87, 16, v87
	v_lshlrev_b32_e32 v86, 16, v86
	v_pk_mul_f32 v[86:87], v[94:95], v[86:87]
	v_bfe_u32 v99, v100, 16, 1
	v_bfe_u32 v94, v91, 16, 1
	v_bfe_u32 v95, v90, 16, 1
	v_bfe_u32 v98, v101, 16, 1
	v_add3_u32 v99, v100, v99, s68
	v_bfe_u32 v100, v86, 16, 1
	v_add3_u32 v98, v101, v98, s68
	v_add3_u32 v90, v90, v95, s68
	v_add3_u32 v91, v91, v94, s68
	v_bfe_u32 v94, v96, 16, 1
	v_bfe_u32 v95, v97, 16, 1
	v_bfe_u32 v101, v87, 16, 1
	v_add3_u32 v86, v86, v100, s68
	v_add3_u32 v87, v87, v101, s68
	v_add3_u32 v95, v97, v95, s68
	v_add3_u32 v94, v96, v94, s68
	v_lshrrev_b32_e32 v86, 16, v86
	s_mov_b32 s0, 0x10928000
	v_lshrrev_b32_e32 v94, 16, v94
	v_lshrrev_b32_e32 v95, 16, v95
	v_lshrrev_b32_e32 v87, 16, v87
	v_and_or_b32 v96, v90, s37, v86
	v_add_co_u32_e32 v86, vcc, s0, v106
	v_and_or_b32 v97, v91, s37, v87
	v_and_or_b32 v95, v98, s37, v95
	v_and_or_b32 v94, v99, s37, v94
	v_addc_co_u32_e32 v87, vcc, 0, v107, vcc
	global_store_dwordx4 v[86:87], v[94:97], off offset:1024
	v_mov_b32_e32 v86, v117
	v_mov_b32_e32 v87, v119
	v_pk_add_f32 v[86:87], v[174:175], v[86:87]
	v_and_b32_e32 v91, 0xffff0000, v83
	v_and_b32_e32 v90, 0xffff0000, v82
	v_mov_b32_e32 v117, v118
	v_pk_mul_f32 v[86:87], v[86:87], v[90:91]
	v_pk_add_f32 v[90:91], v[174:175], v[116:117]
	v_lshlrev_b32_e32 v83, 16, v83
	v_lshlrev_b32_e32 v82, 16, v82
	v_pk_mul_f32 v[82:83], v[90:91], v[82:83]
	v_bfe_u32 v94, v93, 16, 1
	v_bfe_u32 v90, v87, 16, 1
	v_bfe_u32 v91, v86, 16, 1
	v_bfe_u32 v95, v92, 16, 1
	v_add3_u32 v93, v93, v94, s68
	v_bfe_u32 v94, v82, 16, 1
	v_add3_u32 v92, v92, v95, s68
	v_add3_u32 v86, v86, v91, s68
	v_add3_u32 v87, v87, v90, s68
	v_bfe_u32 v90, v80, 16, 1
	v_bfe_u32 v91, v81, 16, 1
	v_bfe_u32 v95, v83, 16, 1
	v_add3_u32 v82, v82, v94, s68
	v_add3_u32 v83, v83, v95, s68
	v_add3_u32 v81, v81, v91, s68
	v_add3_u32 v80, v80, v90, s68
	v_lshrrev_b32_e32 v82, 16, v82
	s_mov_b32 s0, 0x10930000
	v_lshrrev_b32_e32 v80, 16, v80
	v_lshrrev_b32_e32 v81, 16, v81
	v_lshrrev_b32_e32 v83, 16, v83
	v_and_or_b32 v82, v86, s37, v82
	v_add_co_u32_e32 v86, vcc, s0, v106
	v_and_or_b32 v83, v87, s37, v83
	v_and_or_b32 v81, v93, s37, v81
	v_and_or_b32 v80, v92, s37, v80
	v_addc_co_u32_e32 v87, vcc, 0, v107, vcc
	global_store_dwordx4 v[86:87], v[80:83], off offset:1024
	v_lshlrev_b32_e32 v87, 16, v111
	v_lshlrev_b32_e32 v86, 16, v110
	v_mov_b32_e32 v80, v113
	v_mov_b32_e32 v81, v115
	v_pk_add_f32 v[80:81], v[176:177], v[80:81]
	v_and_b32_e32 v83, 0xffff0000, v111
	v_and_b32_e32 v82, 0xffff0000, v110
	v_mov_b32_e32 v113, v114
	v_pk_mul_f32 v[80:81], v[80:81], v[82:83]
	v_pk_add_f32 v[82:83], v[176:177], v[112:113]
	v_bfe_u32 v90, v89, 16, 1
	v_pk_mul_f32 v[82:83], v[82:83], v[86:87]
	v_bfe_u32 v86, v81, 16, 1
	v_bfe_u32 v87, v80, 16, 1
	v_bfe_u32 v91, v88, 16, 1
	v_add3_u32 v88, v88, v91, s68
	v_add3_u32 v89, v89, v90, s68
	v_add3_u32 v80, v80, v87, s68
	v_add3_u32 v81, v81, v86, s68
	v_bfe_u32 v86, v84, 16, 1
	v_bfe_u32 v87, v85, 16, 1
	v_bfe_u32 v90, v82, 16, 1
	v_bfe_u32 v91, v83, 16, 1
	v_add3_u32 v83, v83, v91, s68
	v_add3_u32 v82, v82, v90, s68
	v_add3_u32 v85, v85, v87, s68
	v_add3_u32 v84, v84, v86, s68
	v_lshrrev_b32_e32 v84, 16, v84
	v_lshrrev_b32_e32 v85, 16, v85
	v_lshrrev_b32_e32 v82, 16, v82
	v_lshrrev_b32_e32 v83, 16, v83
	v_and_or_b32 v83, v81, s37, v83
	v_and_or_b32 v82, v80, s37, v82
	v_and_or_b32 v81, v89, s37, v85
	v_and_or_b32 v80, v88, s37, v84
	v_lshl_add_u64 v[84:85], v[180:181], 0, s[20:21]
	global_store_dwordx4 v[84:85], v[80:83], off
	s_waitcnt lgkmcnt(0)
	s_add_u32 s20, s20, 64
	s_addc_u32 s21, s21, 0
	s_cmpk_lg_i32 s20, 0x100
	s_cbranch_scc1 .LBB0_511
	s_add_i32 s5, s5, s77
	s_add_i32 s4, s4, s7
	s_cmp_lt_i32 s5, s2
	s_cbranch_scc1 .LBB0_510
